# S5 pass C loop waits no longer drain stores; removed WG barriers between SSD units and S5 parts in P2/P4 (S5 LDS buffers of waves 4-7 moved into their own sub-block region)
# speedup vs baseline: 1.0109x; 1.0109x over previous
; __device__ __forceinline__ void s5_passA_item(const Args& a, int item, int lane) {
;     const int b = item >> 8, g = (item >> 3) & 31, seg = item & 7;
;     S5Consts c; s5_consts(a, g, lane, c);
;     float hr = 0.f, hi = 0.f;
;     const int row0 = b * SEQ + seg * 1024;
;     const bf16_t* up_ = (const bf16_t*)(a.ws + WS_PROJ) + (size_t)(row0 + (lane & 31)) * NPROJ + 1536 + g * 16 + 8 * (lane >> 5);
;     bf16x8 uf = *(const bf16x8*)up_;
;     for (int blk = 0; blk < 32; ++blk) { const int nb = blk < 31 ? blk + 1 : 31; bf16x8 nuf; s5_block<false>(a, c, uf, lane, hr, hi, nullptr, up_ + (size_t)nb * 32 * NPROJ, nuf); uf = nuf; }
; __global__ void __launch_bounds__(512, 2) fwd_kernel(Args a) {
;     ...
;             __syncthreads();
;         }
;         for (int it = gw; it < NBATCH * 32 * 8; it += NGW) s5_passA_item(a, it, lane);
.LBB0_450:
	v_readlane_b32 s0, v254, 40
	s_cmpk_gt_i32 s0, 0x7ff
	s_cbranch_scc1 .LBB0_471
	v_lshrrev_b32_e32 v0, 2, v177
	v_and_b32_e32 v0, 8, v0
	v_readlane_b32 s4, v254, 43
	v_mov_b32_e32 v85, 0
	v_lshlrev_b32_e32 v84, 2, v0
	v_readlane_b32 s8, v254, 47
	v_readlane_b32 s9, v254, 48
	v_readlane_b32 s10, v254, 49
	v_readlane_b32 s11, v254, 50
	v_lshl_add_u64 v[86:87], s[8:9], 0, v[84:85]
	v_lshrrev_b32_e32 v1, 1, v177
	v_lshl_add_u64 v[88:89], s[10:11], 0, v[84:85]
	v_lshlrev_b32_e32 v84, 2, v176
	v_readlane_b32 s6, v254, 45
	v_lshl_add_u64 v[2:3], s[88:89], 0, v[84:85]
	s_mov_b64 s[2:3], 0x700000
	v_and_b32_e32 v84, 16, v1
	v_lshl_add_u64 v[90:91], v[2:3], 0, s[2:3]
	v_lshl_add_u64 v[2:3], s[88:89], 0, v[84:85]
	s_mov_b64 s[2:3], 0xa820c00
	v_readlane_b32 s6, v254, 39
	v_readlane_b32 s16, v254, 55
	v_lshl_add_u64 v[92:93], v[2:3], 0, s[2:3]
	s_lshl_b32 s2, s96, 8
	s_lshl_b32 s3, s6, 5
	v_readlane_b32 s5, v254, 44
	v_readlane_b32 s18, v254, 57
	s_add_i32 s16, s2, s3
	s_lshl_b32 s2, s96, 13
	s_lshl_b32 s3, s6, 10
	v_readlane_b32 s17, v254, 56
	v_readlane_b32 s19, v254, 58
	v_readlane_b32 s4, v254, 41
	s_add_i32 s18, s2, s3
	v_readlane_b32 s2, v254, 40
	v_and_b32_e32 v106, 31, v177
	v_cmp_gt_u32_e64 s[0:1], 32, v176
	s_lshl_b32 s17, s4, 8
	s_lshl_b32 s19, s4, 13
	s_mov_b32 s20, 0x3fb8aa3b
	s_mov_b32 s21, 0xc2ce8ed0
	s_mov_b32 s9, 0
	s_mov_b32 s23, 0x42b17218
	v_mov_b32_e32 v107, 0x7f800000
	s_brev_b32 s24, 18
	s_mov_b32 s25, 0xfe5163ab
	s_mov_b32 s26, 0x3c439041
	s_mov_b32 s27, 0xdb629599
	s_mov_b32 s28, 0xf534ddc0
	s_mov_b32 s29, 0xfc2757d1
	s_mov_b32 s30, 0x4e441529
	s_mov_b32 s31, 0xa2f9836e
	s_mov_b32 s33, 0x3fc90fda
	s_mov_b32 s34, 0x3f22f983
	s_mov_b32 s35, 0xbfc90fda
	s_movk_i32 s52, 0x1f8
	v_mov_b32_e32 v108, 0xbab64f3b
	v_mov_b32_e32 v109, 0x3c0881c4
	s_brev_b32 s53, 1
	v_lshlrev_b32_e32 v94, 1, v0
	v_not_b32_e32 v110, 63
	v_not_b32_e32 v111, 31
	v_mov_b32_e32 v112, 0x80
	v_mov_b32_e32 v113, 0x7fc00000
	v_mov_b32_e32 v114, 0x800
	s_mov_b32 s10, s2
	v_readlane_b32 s7, v254, 46
	v_readlane_b32 s12, v254, 51
	v_readlane_b32 s13, v254, 52
	v_readlane_b32 s14, v254, 53
	v_readlane_b32 s15, v254, 54
	v_readlane_b32 s5, v254, 42

; #define LAS __attribute__((address_space(3)))
; __device__ __forceinline__ void s5_passC_run(const Args& a, LAS unsigned char* wlds, int row0, int nblk, int g, int lane, float& hr, float& hi) {
;     S5Consts c; s5_consts(a, g, lane, c);
;     const int r16 = lane & 15, q4 = lane >> 4;
; __global__ void __launch_bounds__(512, 2) fwd_kernel(Args a) {
;     ...
;         __syncthreads();
;         LAS unsigned char* wlds = lds + wave * (32 * S5_LD);
;         for (int it = gw; it < NBATCH * 32 * 8 + NBATCH * 32; it += NGW) {
;             if (it < NBATCH * 32 * 8) {
;                 const int b = it >> 8, g = (it >> 3) & 31, seg = it & 7;
;                 const float* hin = (const float*)(ws + WS_S5HIN) + (size_t)it * 128;
;                 float hr = hin[lane], hi = hin[64 + lane];
;                 s5_passC_run(a, wlds, b * SEQ + seg * 1024, 32, g, lane, hr, hi);
.LBB0_853:
	v_readlane_b32 s0, v254, 40
	s_cmpk_gt_i32 s0, 0x8ff
	v_readlane_b32 s96, v254, 59
	v_readlane_b32 s22, v254, 60
	s_cbranch_scc1 .LBB0_893
	v_readlane_b32 s6, v254, 39
	s_mul_i32 s0, s6, 0x2200
	v_mov_b32_e32 v113, 0
	v_lshrrev_b32_e32 v0, 2, v177
	s_add_i32 s18, s0, 0
	s_cmp_gt_u32 s6, 3
	s_cselect_b32 s1, 0xa440, 0
	s_add_i32 s18, s18, s1
	v_and_b32_e32 v114, 8, v0
	v_and_b32_e32 v120, 12, v0
	v_lshlrev_b32_e32 v122, 2, v176
	v_and_b32_e32 v0, 48, v177
	v_mov_b32_e32 v123, v113
	s_add_u32 s10, s88, 0xa800000
	v_add_u32_e32 v159, s18, v0
	v_lshl_add_u64 v[0:1], s[88:89], 0, v[122:123]
	s_mov_b64 s[2:3], 0x800000
	v_readlane_b32 s36, v254, 43
	s_addc_u32 s11, s89, 0
	v_lshl_add_u64 v[124:125], v[0:1], 0, s[2:3]
	s_lshl_b32 s2, s96, 8
	s_lshl_b32 s3, s6, 5
	v_lshlrev_b32_e32 v112, 2, v114
	v_readlane_b32 s40, v254, 47
	v_readlane_b32 s41, v254, 48
	v_readlane_b32 s42, v254, 49
	v_readlane_b32 s43, v254, 50
	s_add_i32 s19, s2, s3
	s_lshl_b32 s2, s96, 13
	s_lshl_b32 s3, s6, 10
	v_lshl_add_u64 v[116:117], s[40:41], 0, v[112:113]
	v_lshl_add_u64 v[118:119], s[42:43], 0, v[112:113]
	v_and_b32_e32 v121, 15, v177
	v_lshlrev_b32_e32 v112, 1, v120
	v_readlane_b32 s4, v254, 41
	s_add_i32 s24, s2, s3
	v_readlane_b32 s2, v254, 40
	s_mov_b32 s9, 0
	v_and_b32_e32 v115, 31, v177
	v_cmp_gt_u32_e64 s[0:1], 32, v176
	v_or_b32_e32 v158, 16, v121
	v_mul_u32_u24_e32 v160, 0x110, v121
	v_lshl_or_b32 v123, v121, 6, v120
	v_lshl_add_u64 v[126:127], s[10:11], 0, v[112:113]
	s_lshl_b32 s23, s4, 8
	s_lshl_b32 s25, s4, 13
	s_mov_b32 s26, 0x3fb8aa3b
	s_mov_b32 s27, 0xc2ce8ed0
	s_mov_b32 s28, 0x42b17218
	s_brev_b32 s29, 18
	s_mov_b32 s30, 0xfe5163ab
	s_mov_b32 s31, 0x3c439041
	s_mov_b32 s33, 0xdb629599
	s_mov_b32 s34, 0xf534ddc0
	s_mov_b32 s35, 0xfc2757d1
	s_mov_b32 s40, 0x4e441529
	s_mov_b32 s41, 0xa2f9836e
	s_mov_b32 s42, 0x3fc90fda
	s_mov_b32 s43, 0x3f22f983
	s_mov_b32 s52, 0xbfc90fda
	s_movk_i32 s53, 0x1f8
	v_mov_b32_e32 v161, 0xbab64f3b
	v_mov_b32_e32 v162, 0x3c0881c4
	s_brev_b32 s54, 1
	v_mov_b32_e32 v163, 0xc0135761
	s_mov_b32 s55, 0x22c00000
	v_mov_b32_e32 v164, 0x7f800000
	v_not_b32_e32 v165, 63
	v_not_b32_e32 v166, 31
	v_mov_b32_e32 v167, 0x80
	v_mov_b32_e32 v168, 0x7fc00000
	v_mov_b32_e32 v169, 0x800
	s_mov_b32 s12, s2
	v_readlane_b32 s37, v254, 44
	v_readlane_b32 s38, v254, 45
	v_readlane_b32 s39, v254, 46
	v_readlane_b32 s44, v254, 51
	v_readlane_b32 s45, v254, 52
	v_readlane_b32 s46, v254, 53
	v_readlane_b32 s47, v254, 54
	v_readlane_b32 s48, v254, 55
	v_readlane_b32 s49, v254, 56
	v_readlane_b32 s50, v254, 57
	v_readlane_b32 s51, v254, 58
	v_readlane_b32 s5, v254, 42
	s_branch .LBB0_856

; __device__ __forceinline__ unsigned pk2(float lo, float hi) { f32x2 v; v.x = lo; v.y = hi; return __builtin_bit_cast(unsigned, __builtin_convertvector(v, hwbf2)); }
; __device__ __forceinline__ void s5_lambda(const Args& a, int g, int p, float& lbr, float& lbi, float& qr, float& qi) {
;     const float lr = a.in[I_LRE][g * 64 + p], li = a.in[I_LIM][g * 64 + p], dt = expf(a.in[I_LDT][g]);
;     const float mag = expf(lr * dt), ang = li * dt;
;     lbr = mag * cosf(ang); lbi = mag * sinf(ang);
;     const float den = lr * lr + li * li;
;     qr = ((lbr - 1.f) * lr + lbi * li) / den; qi = (lbi * lr - (lbr - 1.f) * li) / den;
; }
; __device__ __forceinline__ void s5_consts(const Args& a, int g, int lane, S5Consts& c) {
;     const int r = lane & 31, hf = lane >> 5;
;     float lb0r, lb0i, q0r, q0i, lb1r, lb1i, q1r, q1i;
;     s5_lambda(a, g, r, lb0r, lb0i, q0r, q0i); s5_lambda(a, g, 32 + r, lb1r, lb1i, q1r, q1i);
;     c.lbr = hf ? lb1r : lb0r; c.lbi = hf ? lb1i : lb0i;
; #pragma unroll
;     for (int nb = 0; nb < 4; ++nb) {
;         const int ps = r + 32 * (nb >> 1); const float qr = (nb >> 1) ? q1r : q0r, qi = (nb >> 1) ? q1i : q0i;
;         const float* br = a.in[I_BRE] + (size_t)(g * 64 + ps) * 16 + 8 * hf; const float* bi = a.in[I_BIM] + (size_t)(g * 64 + ps) * 16 + 8 * hf;
;         float v[8];
; #pragma unroll
;         for (int j = 0; j < 8; ++j) v[j] = (nb & 1) ? (qr * bi[j] + qi * br[j]) : (qr * br[j] - qi * bi[j]);
;         u32x4 w; w.x = pk2(v[0], v[1]); w.y = pk2(v[2], v[3]); w.z = pk2(v[4], v[5]); w.w = pk2(v[6], v[7]);
;         c.bb[nb] = __builtin_bit_cast(bf16x8, w);
;     }
; }
.LBB0_891:
	s_or_b64 exec, exec, s[2:3]
	s_waitcnt vmcnt(0)
	v_mul_f32_e32 v19, v4, v10
	v_mul_f32_e32 v20, 0x3fb8aa3b, v19
	v_fma_f32 v21, v19, s26, -v20
	v_rndne_f32_e32 v22, v20
	v_fmac_f32_e32 v21, 0x32a5705f, v19
	v_sub_f32_e32 v20, v20, v22
	v_add_f32_e32 v20, v20, v21
	v_exp_f32_e32 v20, v20
	v_cvt_i32_f32_e32 v21, v22
	s_lshl_b32 s2, s12, 5
	s_lshl_b32 s3, s12, 10
	v_cmp_ngt_f32_e32 vcc, s27, v19
	v_ldexp_f32 v20, v20, v21
	s_and_b32 s2, s2, 0xffffe000
	s_and_b32 s3, s3, 0x1c00
	v_cndmask_b32_e32 v20, 0, v20, vcc
	v_cmp_nlt_f32_e32 vcc, s28, v19
	s_or_b32 s7, s2, s3
	s_and_b32 s2, s19, 0xffffe000
	v_cndmask_b32_e32 v24, v164, v20, vcc
	v_mul_f32_e32 v20, v16, v16
	v_or_b32_e32 v22, s2, v121
	s_and_b32 s2, s24, 0x1c00
	v_fmamk_f32 v21, v20, 0x37d75334, v161
	v_or_b32_e32 v130, s2, v22
	v_fmaak_f32 v21, v20, v21, 0x3d2aabf7
	v_fmamk_f32 v22, v20, 0xb94c1982, v162
	v_fmaak_f32 v21, v20, v21, 0xbf000004
	v_fmaak_f32 v22, v20, v22, 0xbe2aaa9d
	v_fma_f32 v21, v20, v21, 1.0
	v_mul_f32_e32 v20, v20, v22
	v_mul_f32_e32 v4, v8, v4
	v_fmac_f32_e32 v16, v16, v20
	v_mul_f32_e32 v20, 0x3fb8aa3b, v4
	v_fma_f32 v22, v4, s26, -v20
	v_rndne_f32_e32 v23, v20
	v_fmac_f32_e32 v22, 0x32a5705f, v4
	v_sub_f32_e32 v20, v20, v23
	v_add_f32_e32 v20, v20, v22
	v_exp_f32_e32 v20, v20
	v_cvt_i32_f32_e32 v22, v23
	v_lshlrev_b32_e32 v19, 30, v17
	v_and_b32_e32 v17, 1, v17
	v_cmp_eq_u32_e32 vcc, 0, v17
	v_xor_b32_e32 v3, v3, v2
	v_mov_b32_e32 v17, v8
	v_cndmask_b32_e64 v16, -v16, v21, vcc
	v_bitop3_b32 v19, v19, v16, s54 bitop3:0x6c
	v_ldexp_f32 v16, v20, v22
	v_cmp_ngt_f32_e32 vcc, s27, v4
	v_mov_b32_e32 v21, v0
	v_lshlrev_b32_e32 v112, 6, v1
	v_cndmask_b32_e32 v16, 0, v16, vcc
	v_cmp_nlt_f32_e32 vcc, s28, v4
	v_lshlrev_b32_e32 v4, 30, v9
	v_and_b32_e32 v4, 0x80000000, v4
	v_xor_b32_e32 v3, v3, v4
	v_and_b32_e32 v4, 1, v9
	v_mul_f32_e32 v9, v7, v7
	v_cndmask_b32_e32 v22, v164, v16, vcc
	v_fmamk_f32 v16, v9, 0xb94c1982, v162
	v_fmaak_f32 v16, v9, v16, 0xbe2aaa9d
	v_mul_f32_e32 v16, v9, v16
	v_fmac_f32_e32 v7, v7, v16
	v_fmamk_f32 v16, v9, 0x37d75334, v161
	v_fmaak_f32 v16, v9, v16, 0x3d2aabf7
	v_fmaak_f32 v16, v9, v16, 0xbf000004
	v_fma_f32 v9, v9, v16, 1.0
	v_cmp_eq_u32_e32 vcc, 0, v4
	v_readlane_b32 s56, v254, 43
	v_readlane_b32 s64, v254, 51
	v_cndmask_b32_e32 v4, v9, v7, vcc
	v_xor_b32_e32 v3, v3, v4
	v_cmp_class_f32_e64 vcc, v2, s53
	v_mul_f32_e32 v4, v5, v5
	v_fmamk_f32 v7, v4, 0xb94c1982, v162
	v_cndmask_b32_e32 v2, v168, v3, vcc
	v_mul_f32_e32 v16, v22, v2
	v_lshlrev_b32_e32 v2, 30, v6
	v_and_b32_e32 v3, 1, v6
	v_fmamk_f32 v6, v4, 0x37d75334, v161
	v_fmaak_f32 v6, v4, v6, 0x3d2aabf7
	v_fmaak_f32 v6, v4, v6, 0xbf000004
	v_fmaak_f32 v7, v4, v7, 0xbe2aaa9d
	v_fma_f32 v6, v4, v6, 1.0
	v_mul_f32_e32 v4, v4, v7
	v_fmac_f32_e32 v5, v5, v4
	v_cmp_eq_u32_e64 s[2:3], 0, v3
	v_readlane_b32 s65, v254, 52
	v_readlane_b32 s66, v254, 53
	v_cndmask_b32_e64 v3, -v5, v6, s[2:3]
	v_bitop3_b32 v2, v2, v3, s54 bitop3:0x6c
	v_cndmask_b32_e32 v6, v168, v2, vcc
	v_fma_f32 v20, v22, v6, -1.0
	v_pk_mul_f32 v[2:3], v[8:9], v[16:17] op_sel_hi:[0,1]
	v_pk_mul_f32 v[4:5], v[0:1], v[20:21] op_sel_hi:[0,1]
	v_sub_f32_e32 v17, v2, v4
	v_add_f32_e32 v25, v3, v5
	v_div_scale_f32 v2, s[2:3], v25, v25, v17
	v_rcp_f32_e32 v34, v2
	v_cmp_class_f32_e64 s[2:3], v13, s53
	v_mul_f32_e32 v37, v22, v6
	v_mov_b32_e32 v9, v0
	v_fma_f32 v3, -v2, v34, 1.0
	v_fmac_f32_e32 v34, v3, v34
	v_div_scale_f32 v3, vcc, v17, v25, v17
	v_cndmask_b32_e64 v35, v168, v19, s[2:3]
	v_mul_f32_e32 v19, v3, v34
	v_fma_f32 v4, -v2, v19, v3
	v_fmac_f32_e32 v19, v4, v34
	v_lshl_add_u64 v[4:5], v[118:119], 0, v[112:113]
	v_fma_f32 v38, -v2, v19, v3
	v_lshl_add_u64 v[22:23], v[116:117], 0, v[112:113]
	global_load_dwordx4 v[0:3], v[4:5], off offset:16
	global_load_dwordx4 v[26:29], v[4:5], off
	s_nop 0
	global_load_dwordx4 v[4:7], v[22:23], off offset:16
	global_load_dwordx4 v[30:33], v[22:23], off
	v_mov_b32_e32 v21, v16
	v_pk_mul_f32 v[8:9], v[8:9], v[20:21]
	v_xor_b32_e32 v13, v14, v13
	v_add_f32_e32 v21, v8, v9
	v_div_scale_f32 v8, s[4:5], v25, v25, v21
	v_rcp_f32_e32 v22, v8
	v_div_fmas_f32 v9, v38, v34, v19
	v_div_fixup_f32 v20, v9, v25, v17
	v_mov_b32_e32 v14, v11
	v_fma_f32 v9, -v8, v22, 1.0
	v_fmac_f32_e32 v22, v9, v22
	v_div_scale_f32 v9, vcc, v21, v25, v21
	v_mul_f32_e32 v17, v9, v22
	v_fma_f32 v19, -v8, v17, v9
	v_fmac_f32_e32 v17, v19, v22
	v_fma_f32 v23, -v8, v17, v9
	v_mul_f32_e32 v8, v18, v18
	v_fmamk_f32 v9, v8, 0xb94c1982, v162
	v_fmaak_f32 v9, v8, v9, 0xbe2aaa9d
	v_mul_f32_e32 v9, v8, v9
	v_fmac_f32_e32 v18, v18, v9
	v_fmamk_f32 v9, v8, 0x37d75334, v161
	v_fmaak_f32 v9, v8, v9, 0x3d2aabf7
	v_fmaak_f32 v9, v8, v9, 0xbf000004
	v_fma_f32 v8, v8, v9, 1.0
	v_and_b32_e32 v9, 1, v15
	v_cmp_eq_u32_e64 s[4:5], 0, v9
	v_lshlrev_b32_e32 v9, 30, v15
	v_and_b32_e32 v9, 0x80000000, v9
	v_cndmask_b32_e64 v8, v8, v18, s[4:5]
	v_xor_b32_e32 v9, v13, v9
	v_xor_b32_e32 v8, v9, v8
	v_cndmask_b32_e64 v8, v168, v8, s[2:3]
	v_mul_f32_e32 v19, v24, v8
	v_fma_f32 v18, v24, v35, -1.0
	v_pk_mul_f32 v[8:9], v[10:11], v[18:19]
	v_mul_f32_e32 v36, v24, v35
	v_add_f32_e32 v13, v8, v9
	v_mov_b32_e32 v8, v19
	v_mov_b32_e32 v9, v10
	v_pk_mul_f32 v[8:9], v[10:11], v[8:9] op_sel_hi:[0,1]
	v_mov_b32_e32 v10, v18
	v_pk_mul_f32 v[10:11], v[14:15], v[10:11] op_sel_hi:[0,1]
	v_add_f32_e32 v9, v9, v11
	v_div_scale_f32 v11, s[2:3], v9, v9, v13
	v_rcp_f32_e32 v14, v11
	v_div_fmas_f32 v15, v23, v22, v17
	v_div_fixup_f32 v24, v15, v25, v21
	v_sub_f32_e32 v8, v8, v10
	v_fma_f32 v15, -v11, v14, 1.0
	v_fmac_f32_e32 v14, v15, v14
	v_div_scale_f32 v15, vcc, v13, v9, v13
	v_mul_f32_e32 v17, v15, v14
	v_fma_f32 v18, -v11, v17, v15
	v_fmac_f32_e32 v17, v18, v14
	v_div_scale_f32 v10, s[2:3], v9, v9, v8
	v_fma_f32 v11, -v11, v17, v15
	v_rcp_f32_e32 v15, v10
	v_div_fmas_f32 v11, v11, v14, v17
	v_div_fixup_f32 v18, v11, v9, v13
	v_lshl_or_b32 v112, v12, 6, v169
	v_fma_f32 v11, -v10, v15, 1.0
	v_fmac_f32_e32 v15, v11, v15
	v_div_scale_f32 v11, vcc, v8, v9, v8
	v_mul_f32_e32 v13, v11, v15
	v_fma_f32 v14, -v10, v13, v11
	v_fmac_f32_e32 v13, v14, v15
	v_fma_f32 v10, -v10, v13, v11
	v_div_fmas_f32 v10, v10, v15, v13
	v_div_fixup_f32 v22, v10, v9, v8
	v_lshlrev_b32_e32 v17, 2, v123
	s_waitcnt vmcnt(2)
; __device__ __forceinline__ void s5_consts(const Args& a, int g, int lane, S5Consts& c) {
;     ...
;     for (int nb = 0; nb < 4; ++nb) {
;         const int ps = r + 32 * (nb >> 1); const float qr = (nb >> 1) ? q1r : q0r, qi = (nb >> 1) ? q1i : q0i;
;         const float* br = a.in[I_BRE] + (size_t)(g * 64 + ps) * 16 + 8 * hf; const float* bi = a.in[I_BIM] + (size_t)(g * 64 + ps) * 16 + 8 * hf;
;         float v[8];
; #pragma unroll
;         for (int j = 0; j < 8; ++j) v[j] = (nb & 1) ? (qr * bi[j] + qi * br[j]) : (qr * br[j] - qi * bi[j]);
;         u32x4 w; w.x = pk2(v[0], v[1]); w.y = pk2(v[2], v[3]); w.z = pk2(v[4], v[5]); w.w = pk2(v[6], v[7]);
;         c.bb[nb] = __builtin_bit_cast(bf16x8, w);
;     }
; }
; __device__ __forceinline__ void s5_passC_run(const Args& a, LAS unsigned char* wlds, int row0, int nblk, int g, int lane, float& hr, float& hi) {
;     S5Consts c; s5_consts(a, g, lane, c);
;     const int r16 = lane & 15, q4 = lane >> 4;
;     bf16x8 ca[4];
; #pragma unroll
;     for (int kb = 0; kb < 4; ++kb) { float v[8];
; #pragma unroll
;         for (int j = 0; j < 8; ++j) { const int comp = 32 * kb + 8 * q4 + j, p = comp >> 1; v[j] = (comp & 1) ? -a.in[I_CIM][(size_t)(g * 16 + r16) * 64 + p] : a.in[I_CRE][(size_t)(g * 16 + r16) * 64 + p]; }
;         u32x4 w; w.x = pk2(v[0], v[1]); w.y = pk2(v[2], v[3]); w.z = pk2(v[4], v[5]); w.w = pk2(v[6], v[7]); ca[kb] = __builtin_bit_cast(bf16x8, w); }
;     bf16x4 ga[2];
; #pragma unroll
;     for (int mb = 0; mb < 2; ++mb) { float v[4];
; #pragma unroll
;         for (int j = 0; j < 4; ++j) v[j] = a.in[I_GLUW][(size_t)(g * 16 + 4 * q4 + j) * 32 + mb * 16 + r16];
;         u32x2 w; w.x = pk2(v[0], v[1]); w.y = pk2(v[2], v[3]); ga[mb] = __builtin_bit_cast(bf16x4, w); }
;     f32x4 dD, gb0, gb1;
; #pragma unroll
;     for (int j = 0; j < 4; ++j) { dD[j] = a.in[I_S5D][g * 16 + 4 * q4 + j]; gb0[j] = a.in[I_GLUB][g * 32 + 4 * q4 + j]; gb1[j] = a.in[I_GLUB][g * 32 + 16 + 4 * q4 + j]; }
;     const bf16_t* proj = (const bf16_t*)(a.ws + WS_PROJ);
;     bf16_t* mixin = (bf16_t*)(a.ws + WS_MIXIN);
;     const bf16_t* up_ = proj + (size_t)(row0 + (lane & 31)) * NPROJ + 1536 + g * 16 + 8 * (lane >> 5);
;     bf16x8 uf = *(const bf16x8*)up_;
;     u32x2 uus[2], uun[2];
; #pragma unroll
;     for (int sb = 0; sb < 2; ++sb) uus[sb] = *(const u32x2*)(proj + (size_t)(row0 + sb * 16 + r16) * NPROJ + 1536 + g * 16 + 4 * q4);
	v_pk_mul_f32 v[8:9], v[20:21], v[26:27] op_sel_hi:[0,1]
	v_pk_mul_f32 v[26:27], v[24:25], v[26:27] op_sel_hi:[0,1]
	s_waitcnt vmcnt(0)
	v_pk_fma_f32 v[42:43], v[24:25], v[30:31], v[8:9] op_sel_hi:[0,1,1] neg_lo:[0,0,1] neg_hi:[0,0,1]
	v_pk_fma_f32 v[30:31], v[20:21], v[30:31], v[26:27] op_sel_hi:[0,1,1]
	v_pk_mul_f32 v[26:27], v[20:21], v[28:29] op_sel_hi:[0,1]
	v_pk_fma_f32 v[26:27], v[24:25], v[32:33], v[26:27] op_sel_hi:[0,1,1] neg_lo:[0,0,1] neg_hi:[0,0,1]
	v_lshl_add_u64 v[38:39], v[116:117], 0, v[112:113]
	v_lshl_add_u64 v[12:13], v[118:119], 0, v[112:113]
	v_cvt_pk_bf16_f32 v65, v26, v27
	v_pk_mul_f32 v[26:27], v[24:25], v[28:29] op_sel_hi:[0,1]
	v_lshl_or_b32 v17, s8, 12, v17
	v_readlane_b32 s67, v254, 54
	v_readlane_b32 s68, v254, 55
	v_readlane_b32 s69, v254, 56
	v_readlane_b32 s70, v254, 57
	v_readlane_b32 s71, v254, 58
	s_mov_b64 s[44:45], s[64:65]
	s_lshl_b32 s2, s8, 4
	v_cndmask_b32_e64 v132, v36, v37, s[0:1]
	global_load_dwordx4 v[8:11], v[12:13], off offset:16
	global_load_dwordx4 v[34:37], v[12:13], off
	s_nop 0
	global_load_dwordx4 v[12:15], v[38:39], off offset:16
	s_nop 0
	global_load_dwordx4 v[38:41], v[38:39], off
	v_cvt_pk_bf16_f32 v64, v42, v43
	v_pk_fma_f32 v[46:47], v[20:21], v[32:33], v[26:27] op_sel_hi:[0,1,1]
	s_mov_b64 s[46:47], s[66:67]
	global_load_dwordx4 v[26:29], v17, s[44:45]
	global_load_dwordx4 v[42:45], v17, s[46:47]
	global_load_dwordx4 v[50:53], v17, s[44:45] offset:64
	global_load_dwordx4 v[54:57], v17, s[46:47] offset:64
	global_load_dwordx4 v[58:61], v17, s[44:45] offset:128
	global_load_dwordx4 v[104:107], v17, s[46:47] offset:128
	global_load_dwordx4 v[108:111], v17, s[44:45] offset:192
	global_load_dwordx4 v[138:141], v17, s[46:47] offset:192
	v_or_b32_e32 v17, s2, v120
	v_lshlrev_b32_e32 v21, 5, v17
	v_or_b32_e32 v23, v21, v121
	v_readlane_b32 s57, v254, 44
	v_readlane_b32 s58, v254, 45
	v_readlane_b32 s59, v254, 46
	v_readlane_b32 s60, v254, 47
	v_readlane_b32 s61, v254, 48
	v_readlane_b32 s62, v254, 49
	v_readlane_b32 s63, v254, 50
	v_lshlrev_b32_e32 v23, 2, v23
	v_or_b32_e32 v21, v21, v158
	s_lshl_b32 s8, s8, 5
	s_mov_b64 s[48:49], s[68:69]
	s_mov_b64 s[50:51], s[70:71]
	v_or_b32_e32 v25, 0x100, v23
	v_lshlrev_b32_e32 v21, 2, v21
	v_or_b32_e32 v32, s8, v120
	v_readlane_b32 s56, v254, 23
	global_load_dword v131, v23, s[50:51]
	global_load_dword v133, v23, s[50:51] offset:128
	global_load_dword v142, v25, s[50:51]
	global_load_dword v143, v21, s[50:51] offset:128
	s_nop 0
	global_load_dword v21, v21, s[50:51] offset:384
	s_nop 0
	global_load_dword v25, v25, s[50:51] offset:64
	s_nop 0
	global_load_dword v144, v23, s[50:51] offset:384
	s_nop 0
	global_load_dword v23, v23, s[50:51] offset:64
	v_lshlrev_b32_e32 v17, 2, v17
	v_lshlrev_b32_e32 v32, 2, v32
	v_readlane_b32 s57, v254, 24
	global_load_dwordx4 v[68:71], v17, s[48:49]
	s_nop 3
	global_load_dwordx4 v[72:75], v32, s[56:57]
	global_load_dwordx4 v[76:79], v32, s[56:57] offset:64
	v_or_b32_e32 v32, s7, v115
	v_ashrrev_i32_e32 v33, 31, v32
	v_lshlrev_b64 v[32:33], 12, v[32:33]
	v_or_b32_e32 v136, s7, v121
	v_lshl_add_u64 v[32:33], s[10:11], 0, v[32:33]
	v_or_b32_e32 v48, 16, v136
	v_lshl_add_u64 v[32:33], v[32:33], 0, s[8:9]
	v_lshlrev_b32_e32 v112, 1, v114
	v_ashrrev_i32_e32 v137, 31, v136
	v_ashrrev_i32_e32 v49, 31, v48
	v_lshl_add_u64 v[134:135], v[32:33], 0, v[112:113]
	v_lshlrev_b64 v[32:33], 12, v[136:137]
	v_lshlrev_b64 v[48:49], 12, v[48:49]
	v_lshl_add_u64 v[32:33], s[10:11], 0, v[32:33]
	v_lshl_add_u64 v[48:49], s[10:11], 0, v[48:49]
	v_lshl_add_u64 v[32:33], v[32:33], 0, s[8:9]
	v_lshlrev_b32_e32 v112, 1, v120
	v_lshl_add_u64 v[48:49], v[48:49], 0, s[8:9]
	v_lshl_add_u64 v[32:33], v[32:33], 0, v[112:113]
	v_lshl_add_u64 v[48:49], v[48:49], 0, v[112:113]
	global_load_dwordx4 v[88:91], v[134:135], off offset:3072
	s_nop 0
	global_load_dwordx2 v[32:33], v[32:33], off offset:3072
	s_nop 0
	global_load_dwordx2 v[48:49], v[48:49], off offset:3072
	s_mov_b32 s6, 0
	v_cvt_pk_bf16_f32 v80, v30, v31
	v_cvt_pk_bf16_f32 v81, v46, v47
	s_lshl_b32 s2, s2, 1
	v_readlane_b32 s58, v254, 25
	v_readlane_b32 s59, v254, 26
	v_readlane_b32 s60, v254, 27
	v_readlane_b32 s61, v254, 28
	v_readlane_b32 s62, v254, 29
	v_readlane_b32 s63, v254, 30
	v_readlane_b32 s64, v254, 31
	v_readlane_b32 s65, v254, 32
	v_readlane_b32 s66, v254, 33
	v_readlane_b32 s67, v254, 34
	v_readlane_b32 s68, v254, 35
	v_readlane_b32 s69, v254, 36
	v_readlane_b32 s70, v254, 37
	v_readlane_b32 s71, v254, 38
	s_waitcnt vmcnt(9)
	v_pk_mul_f32 v[62:63], v[20:21], v[0:1] op_sel_hi:[0,1]
	s_waitcnt vmcnt(8)
	v_pk_mul_f32 v[0:1], v[24:25], v[0:1] op_sel_hi:[0,1]
	v_pk_fma_f32 v[62:63], v[24:25], v[4:5], v[62:63] op_sel_hi:[0,1,1] neg_lo:[0,0,1] neg_hi:[0,0,1]
	v_pk_fma_f32 v[0:1], v[20:21], v[4:5], v[0:1] op_sel_hi:[0,1,1]
	v_pk_mul_f32 v[4:5], v[20:21], v[2:3] op_sel_hi:[0,1]
	v_pk_mul_f32 v[2:3], v[24:25], v[2:3] op_sel_hi:[0,1]
	v_pk_fma_f32 v[2:3], v[20:21], v[6:7], v[2:3] op_sel_hi:[0,1,1]
	v_cvt_pk_bf16_f32 v82, v0, v1
	v_cvt_pk_bf16_f32 v83, v2, v3
	s_waitcnt vmcnt(6)
; #define LAS __attribute__((address_space(3)))
; #define MFMA32(a, b, c) __builtin_amdgcn_mfma_f32_32x32x16_bf16((a), (b), (c), 0, 0, 0)
; template <bool STORE>
; __device__ __forceinline__ void s5_block(const Args& a, const S5Consts& c, const bf16x8 uf, int lane, float& hr, float& hi, LAS unsigned char* wl, const bf16_t* nxt, bf16x8& nuf) {
;     f32x16 bu[4];
; #pragma unroll
;     for (int nb = 0; nb < 4; ++nb) bu[nb] = MFMA32(uf, c.bb[nb], zero16());
;     asm volatile("" ::: "memory");
;     nuf = *(const bf16x8*)nxt;
;     asm volatile("" ::: "memory");
; #pragma unroll
;     for (int i = 0; i < 16; ++i) {
;         auto s0 = __builtin_amdgcn_permlane32_swap(__float_as_uint(bu[0][i]), __float_as_uint(bu[2][i]), false, false);
;         auto s1 = __builtin_amdgcn_permlane32_swap(__float_as_uint(bu[1][i]), __float_as_uint(bu[3][i]), false, false);
;         bu[0][i] = __uint_as_float(s0[0]); bu[2][i] = __uint_as_float(s0[1]); bu[1][i] = __uint_as_float(s1[0]); bu[3][i] = __uint_as_float(s1[1]);
;     }
;     const float nlbi = -c.lbi;
; #pragma unroll
;     for (int ib = 0; ib < 4; ++ib) {
; #pragma unroll
;         for (int j = 0; j < 4; ++j) { const float nr = __builtin_fmaf(c.lbr, hr, __builtin_fmaf(nlbi, hi, bu[0][4 * ib + j])), ni = __builtin_fmaf(c.lbr, hi, __builtin_fmaf(c.lbi, hr, bu[1][4 * ib + j])); hr = nr; hi = ni; if (STORE) *(LAS unsigned*)(wl + (8 * ib + j) * 272 + lane * 4) = pk2(hr, hi); }
; __device__ __forceinline__ void s5_passC_run(const Args& a, LAS unsigned char* wlds, int row0, int nblk, int g, int lane, float& hr, float& hi) {
;     ...
;     for (int kb = 0; kb < 4; ++kb) { float v[8];
; #pragma unroll
;         for (int j = 0; j < 8; ++j) { const int comp = 32 * kb + 8 * q4 + j, p = comp >> 1; v[j] = (comp & 1) ? -a.in[I_CIM][(size_t)(g * 16 + r16) * 64 + p] : a.in[I_CRE][(size_t)(g * 16 + r16) * 64 + p]; }
;         u32x4 w; w.x = pk2(v[0], v[1]); w.y = pk2(v[2], v[3]); w.z = pk2(v[4], v[5]); w.w = pk2(v[6], v[7]); ca[kb] = __builtin_bit_cast(bf16x8, w); }
;     bf16x4 ga[2];
; #pragma unroll
;     for (int mb = 0; mb < 2; ++mb) { float v[4];
; #pragma unroll
;         for (int j = 0; j < 4; ++j) v[j] = a.in[I_GLUW][(size_t)(g * 16 + 4 * q4 + j) * 32 + mb * 16 + r16];
;         u32x2 w; w.x = pk2(v[0], v[1]); w.y = pk2(v[2], v[3]); ga[mb] = __builtin_bit_cast(bf16x4, w); }
	v_pk_mul_f32 v[0:1], v[22:23], v[34:35] op_sel_hi:[0,1]
	v_pk_mul_f32 v[2:3], v[22:23], v[36:37] op_sel_hi:[0,1]
	v_pk_fma_f32 v[0:1], v[18:19], v[38:39], v[0:1] op_sel_hi:[0,1,1] neg_lo:[0,0,1] neg_hi:[0,0,1]
	v_pk_fma_f32 v[2:3], v[18:19], v[40:41], v[2:3] op_sel_hi:[0,1,1] neg_lo:[0,0,1] neg_hi:[0,0,1]
	v_cvt_pk_bf16_f32 v84, v0, v1
	v_pk_mul_f32 v[0:1], v[18:19], v[34:35] op_sel_hi:[0,1]
	v_cvt_pk_bf16_f32 v85, v2, v3
	v_pk_mul_f32 v[2:3], v[18:19], v[36:37] op_sel_hi:[0,1]
	v_pk_fma_f32 v[4:5], v[24:25], v[6:7], v[4:5] op_sel_hi:[0,1,1] neg_lo:[0,0,1] neg_hi:[0,0,1]
	v_pk_fma_f32 v[0:1], v[22:23], v[38:39], v[0:1] op_sel_hi:[0,1,1]
	v_pk_fma_f32 v[2:3], v[22:23], v[40:41], v[2:3] op_sel_hi:[0,1,1]
	v_cvt_pk_bf16_f32 v67, v4, v5
	v_pk_mul_f32 v[4:5], v[22:23], v[8:9] op_sel_hi:[0,1]
	v_pk_mul_f32 v[6:7], v[22:23], v[10:11] op_sel_hi:[0,1]
	v_cvt_pk_bf16_f32 v92, v0, v1
	v_cvt_pk_bf16_f32 v93, v2, v3
	v_xor_b32_e32 v0, 0x80000000, v42
	v_xor_b32_e32 v1, 0x80000000, v43
	v_xor_b32_e32 v2, 0x80000000, v44
	v_xor_b32_e32 v3, 0x80000000, v45
	v_pk_fma_f32 v[4:5], v[18:19], v[12:13], v[4:5] op_sel_hi:[0,1,1] neg_lo:[0,0,1] neg_hi:[0,0,1]
	v_pk_fma_f32 v[6:7], v[18:19], v[14:15], v[6:7] op_sel_hi:[0,1,1] neg_lo:[0,0,1] neg_hi:[0,0,1]
	v_cvt_pk_bf16_f32 v96, v26, v0
	v_cvt_pk_bf16_f32 v97, v27, v1
	v_cvt_pk_bf16_f32 v98, v28, v2
	v_cvt_pk_bf16_f32 v99, v29, v3
	v_xor_b32_e32 v0, 0x80000000, v54
	v_xor_b32_e32 v1, 0x80000000, v55
	v_xor_b32_e32 v2, 0x80000000, v56
	v_xor_b32_e32 v3, 0x80000000, v57
	v_cvt_pk_bf16_f32 v86, v4, v5
	v_pk_mul_f32 v[4:5], v[18:19], v[8:9] op_sel_hi:[0,1]
	v_cvt_pk_bf16_f32 v87, v6, v7
	v_pk_mul_f32 v[6:7], v[18:19], v[10:11] op_sel_hi:[0,1]
	v_cvt_pk_bf16_f32 v100, v50, v0
	v_cvt_pk_bf16_f32 v101, v51, v1
	v_cvt_pk_bf16_f32 v102, v52, v2
	v_cvt_pk_bf16_f32 v103, v53, v3
	v_xor_b32_e32 v0, 0x80000000, v104
	v_xor_b32_e32 v1, 0x80000000, v105
	v_xor_b32_e32 v2, 0x80000000, v106
	v_xor_b32_e32 v3, 0x80000000, v107
	v_pk_fma_f32 v[4:5], v[22:23], v[12:13], v[4:5] op_sel_hi:[0,1,1]
	v_pk_fma_f32 v[6:7], v[22:23], v[14:15], v[6:7] op_sel_hi:[0,1,1]
	v_cvt_pk_bf16_f32 v104, v58, v0
	v_cvt_pk_bf16_f32 v105, v59, v1
	v_cvt_pk_bf16_f32 v106, v60, v2
	v_cvt_pk_bf16_f32 v107, v61, v3
	v_xor_b32_e32 v0, 0x80000000, v138
	v_xor_b32_e32 v1, 0x80000000, v139
	v_xor_b32_e32 v2, 0x80000000, v140
	v_xor_b32_e32 v3, 0x80000000, v141
	v_cvt_pk_bf16_f32 v139, v142, v144
	v_cndmask_b32_e64 v142, v19, v16, s[0:1]
	v_cvt_pk_bf16_f32 v66, v62, v63
	v_cvt_pk_bf16_f32 v94, v4, v5
	v_cvt_pk_bf16_f32 v95, v6, v7
	v_cvt_pk_bf16_f32 v108, v108, v0
	v_cvt_pk_bf16_f32 v109, v109, v1
	v_cvt_pk_bf16_f32 v110, v110, v2
	v_cvt_pk_bf16_f32 v111, v111, v3
	v_cvt_pk_bf16_f32 v138, v131, v133
	v_cvt_pk_bf16_f32 v140, v23, v143
	v_cvt_pk_bf16_f32 v141, v25, v21
	v_xor_b32_e32 v143, 0x80000000, v142
	v_mov_b32_e32 v133, v132
	v_lshl_add_u64 v[144:145], v[126:127], 0, s[8:9]
	s_waitcnt vmcnt(0)
.LBB0_892:
	s_waitcnt vmcnt(2)
	v_mfma_f32_32x32x16_bf16 v[0:15], v[88:91], v[80:83], 0
	v_lshlrev_b32_e32 v150, 16, v48
	v_and_b32_e32 v151, 0xffff0000, v48
	v_lshlrev_b32_e32 v154, 16, v49
	v_and_b32_e32 v155, 0xffff0000, v49
	v_lshlrev_b32_e32 v146, 16, v32
	v_and_b32_e32 v147, 0xffff0000, v32
	v_lshlrev_b32_e32 v148, 16, v33
	v_mfma_f32_32x32x16_bf16 v[48:63], v[88:91], v[92:95], 0
	v_and_b32_e32 v149, 0xffff0000, v33
	s_add_i32 s4, s6, 1
	s_cmp_lt_u32 s6, 31
	v_ashrrev_i32_e32 v131, 31, v130
	s_cselect_b32 s8, s4, s6
	s_lshl_b64 s[6:7], s[8:9], 17
	v_mfma_f32_32x32x16_bf16 v[16:31], v[88:91], v[64:67], 0
	s_nop 4
	v_permlane32_swap_b32_e32 v0, v48
	v_fmac_f32_e32 v0, v142, v129
	v_fmac_f32_e32 v0, v132, v128
	v_permlane32_swap_b32_e32 v1, v49
	v_permlane32_swap_b32_e32 v2, v50
	v_mfma_f32_32x32x16_bf16 v[32:47], v[88:91], v[84:87], 0
	v_permlane32_swap_b32_e32 v3, v51
	v_lshlrev_b64 v[88:89], 11, v[130:131]
	v_add_u32_e32 v137, s18, v122
	v_lshl_add_u64 v[170:171], s[88:89], 0, v[88:89]
	v_lshl_add_u64 v[88:89], v[134:135], 0, s[6:7]
	global_load_dwordx4 v[88:91], v[88:89], off offset:3072
	s_nop 5
	v_permlane32_swap_b32_e32 v16, v32
	v_permlane32_swap_b32_e32 v17, v33
	v_fma_f32 v16, -v142, v128, v16
	v_fmac_f32_e32 v16, v132, v129
	v_fma_f32 v17, -v142, v0, v17
	v_fmac_f32_e32 v1, v142, v16
	v_fmac_f32_e32 v17, v132, v16
	v_permlane32_swap_b32_e32 v18, v34
	v_fmac_f32_e32 v1, v132, v0
	v_fmac_f32_e32 v2, v142, v17
	v_permlane32_swap_b32_e32 v19, v35
	v_cvt_pk_bf16_f32 v128, v16, v0
	v_fma_f32 v16, -v142, v1, v18
	v_fmac_f32_e32 v2, v132, v1
	v_cvt_pk_bf16_f32 v0, v17, v1
	v_fmac_f32_e32 v16, v132, v17
	v_fma_f32 v1, -v142, v2, v19
	v_fmac_f32_e32 v3, v142, v16
	v_fmac_f32_e32 v1, v132, v16
	v_fmac_f32_e32 v3, v132, v2
	v_fmac_f32_e32 v48, v142, v1
	ds_write2_b32 v137, v128, v0 offset1:68
	v_cvt_pk_bf16_f32 v0, v16, v2
	v_fma_f32 v16, -v142, v3, v32
	v_fmac_f32_e32 v48, v132, v3
	v_cvt_pk_bf16_f32 v2, v1, v3
	v_fmac_f32_e32 v16, v132, v1
	v_fma_f32 v1, -v142, v48, v33
	v_fmac_f32_e32 v49, v142, v16
	v_fmac_f32_e32 v1, v132, v16
	v_fmac_f32_e32 v49, v132, v48
	v_fmac_f32_e32 v50, v142, v1
	v_fma_f32 v3, -v142, v49, v34
	v_fmac_f32_e32 v50, v132, v49
	ds_write2_b32 v137, v0, v2 offset0:136 offset1:204
	v_cvt_pk_bf16_f32 v2, v1, v49
	v_fmac_f32_e32 v3, v132, v1
	v_fma_f32 v1, -v142, v50, v35
	v_permlane32_swap_b32_e32 v4, v52
	v_fmac_f32_e32 v51, v142, v3
	v_fmac_f32_e32 v1, v132, v3
	v_add_u32_e32 v175, 0x400, v137
	v_permlane32_swap_b32_e32 v20, v36
	v_cvt_pk_bf16_f32 v0, v16, v48
	v_fmac_f32_e32 v51, v132, v50
	v_fmac_f32_e32 v4, v142, v1
	v_permlane32_swap_b32_e32 v21, v37
	ds_write2_b32 v175, v0, v2 offset0:16 offset1:84
	v_cvt_pk_bf16_f32 v0, v3, v50
; #define LAS __attribute__((address_space(3)))
; __device__ __forceinline__ unsigned pk2(float lo, float hi) { f32x2 v; v.x = lo; v.y = hi; return __builtin_bit_cast(unsigned, __builtin_convertvector(v, hwbf2)); }
; template <bool STORE>
; __device__ __forceinline__ void s5_block(const Args& a, const S5Consts& c, const bf16x8 uf, int lane, float& hr, float& hi, LAS unsigned char* wl, const bf16_t* nxt, bf16x8& nuf) {
;     ...
; #pragma unroll
;     for (int ib = 0; ib < 4; ++ib) {
; #pragma unroll
;         for (int j = 0; j < 4; ++j) { const float nr = __builtin_fmaf(c.lbr, hr, __builtin_fmaf(nlbi, hi, bu[0][4 * ib + j])), ni = __builtin_fmaf(c.lbr, hi, __builtin_fmaf(c.lbi, hr, bu[1][4 * ib + j])); hr = nr; hi = ni; if (STORE) *(LAS unsigned*)(wl + (8 * ib + j) * 272 + lane * 4) = pk2(hr, hi); }
; #pragma unroll
;         for (int j = 0; j < 4; ++j) { const float nr = __builtin_fmaf(c.lbr, hr, __builtin_fmaf(nlbi, hi, bu[2][4 * ib + j])), ni = __builtin_fmaf(c.lbr, hi, __builtin_fmaf(c.lbi, hr, bu[3][4 * ib + j])); hr = nr; hi = ni; if (STORE) *(LAS unsigned*)(wl + (8 * ib + 4 + j) * 272 + lane * 4) = pk2(hr, hi); }
;     }
; __device__ __forceinline__ void s5_passC_run(const Args& a, LAS unsigned char* wlds, int row0, int nblk, int g, int lane, float& hr, float& hi) {
;     ...
;     for (int blk = 0; blk < nblk; ++blk) {
;         const int rb = row0 + blk * 32;
;         const int nb = blk < nblk - 1 ? blk + 1 : blk; bf16x8 nuf;
;         s5_block<true>(a, c, uf, lane, hr, hi, wlds, up_ + (size_t)nb * 32 * NPROJ, nuf); uf = nuf;
; #pragma unroll
;         for (int sb = 0; sb < 2; ++sb) uun[sb] = *(const u32x2*)(proj + (size_t)(row0 + nb * 32 + sb * 16 + r16) * NPROJ + 1536 + g * 16 + 4 * q4);
	v_fma_f32 v3, -v142, v51, v20
	v_fmac_f32_e32 v4, v132, v51
	v_permlane32_swap_b32_e32 v5, v53
	v_cvt_pk_bf16_f32 v2, v1, v51
	v_fmac_f32_e32 v3, v132, v1
	v_fma_f32 v1, -v142, v4, v21
	v_permlane32_swap_b32_e32 v6, v54
	v_fmac_f32_e32 v5, v142, v3
	v_fmac_f32_e32 v1, v132, v3
	v_permlane32_swap_b32_e32 v22, v38
	v_fmac_f32_e32 v5, v132, v4
	v_fmac_f32_e32 v6, v142, v1
	v_permlane32_swap_b32_e32 v23, v39
	ds_write2_b32 v175, v0, v2 offset0:152 offset1:220
	v_cvt_pk_bf16_f32 v0, v3, v4
	v_fma_f32 v3, -v142, v5, v22
	v_fmac_f32_e32 v6, v132, v5
	v_permlane32_swap_b32_e32 v7, v55
	v_cvt_pk_bf16_f32 v2, v1, v5
	v_fmac_f32_e32 v3, v132, v1
	v_fma_f32 v1, -v142, v6, v23
	v_fmac_f32_e32 v7, v142, v3
	v_fmac_f32_e32 v1, v132, v3
	v_add_u32_e32 v178, 0x800, v137
	v_fmac_f32_e32 v7, v132, v6
	v_fmac_f32_e32 v52, v142, v1
	ds_write2_b32 v178, v0, v2 offset0:32 offset1:100
	v_cvt_pk_bf16_f32 v0, v3, v6
	v_fma_f32 v3, -v142, v7, v36
	v_fmac_f32_e32 v52, v132, v7
	v_cvt_pk_bf16_f32 v2, v1, v7
	v_fmac_f32_e32 v3, v132, v1
	v_fma_f32 v1, -v142, v52, v37
	v_fmac_f32_e32 v53, v142, v3
	v_fmac_f32_e32 v1, v132, v3
	v_fmac_f32_e32 v53, v132, v52
	v_fmac_f32_e32 v54, v142, v1
	ds_write2_b32 v178, v0, v2 offset0:168 offset1:236
	v_cvt_pk_bf16_f32 v0, v3, v52
	v_fma_f32 v3, -v142, v53, v38
	v_fmac_f32_e32 v54, v132, v53
	v_cvt_pk_bf16_f32 v2, v1, v53
	v_fmac_f32_e32 v3, v132, v1
	v_fma_f32 v1, -v142, v54, v39
	v_permlane32_swap_b32_e32 v8, v56
	v_fmac_f32_e32 v55, v142, v3
	v_fmac_f32_e32 v1, v132, v3
	v_add_u32_e32 v179, 0xc00, v137
	v_permlane32_swap_b32_e32 v24, v40
	v_fmac_f32_e32 v55, v132, v54
	v_fmac_f32_e32 v8, v142, v1
	v_permlane32_swap_b32_e32 v25, v41
	ds_write2_b32 v179, v0, v2 offset0:48 offset1:116
	v_cvt_pk_bf16_f32 v0, v3, v54
	v_fma_f32 v3, -v142, v55, v24
	v_fmac_f32_e32 v8, v132, v55
	v_permlane32_swap_b32_e32 v9, v57
	v_cvt_pk_bf16_f32 v2, v1, v55
	v_fmac_f32_e32 v3, v132, v1
	v_fma_f32 v1, -v142, v8, v25
	v_permlane32_swap_b32_e32 v10, v58
	v_fmac_f32_e32 v9, v142, v3
	v_fmac_f32_e32 v1, v132, v3
	v_permlane32_swap_b32_e32 v26, v42
	v_fmac_f32_e32 v9, v132, v8
	v_fmac_f32_e32 v10, v142, v1
	v_permlane32_swap_b32_e32 v27, v43
	ds_write2_b32 v179, v0, v2 offset0:184 offset1:252
	v_cvt_pk_bf16_f32 v0, v3, v8
	v_fma_f32 v3, -v142, v9, v26
	v_fmac_f32_e32 v10, v132, v9
	v_add_u32_e32 v152, 16, v130
	v_permlane32_swap_b32_e32 v11, v59
	v_cvt_pk_bf16_f32 v2, v1, v9
	v_fmac_f32_e32 v3, v132, v1
	v_fma_f32 v1, -v142, v10, v27
	v_ashrrev_i32_e32 v153, 31, v152
	v_fmac_f32_e32 v11, v142, v3
	v_fmac_f32_e32 v1, v132, v3
	v_add_u32_e32 v180, 0x1000, v137
	v_lshlrev_b64 v[172:173], 11, v[152:153]
	v_lshl_add_u32 v152, s8, 5, v136
	v_fmac_f32_e32 v11, v132, v10
	v_fmac_f32_e32 v56, v142, v1
	v_or_b32_e32 v156, 16, v152
	ds_write2_b32 v180, v0, v2 offset0:64 offset1:132
	v_cvt_pk_bf16_f32 v0, v3, v10
	v_fma_f32 v3, -v142, v11, v40
	v_fmac_f32_e32 v56, v132, v11
	v_ashrrev_i32_e32 v153, 31, v152
	v_ashrrev_i32_e32 v157, 31, v156
	v_cvt_pk_bf16_f32 v2, v1, v11
	v_fmac_f32_e32 v3, v132, v1
	v_fma_f32 v1, -v142, v56, v41
	v_lshlrev_b64 v[152:153], 12, v[152:153]
	v_lshlrev_b64 v[156:157], 12, v[156:157]
	v_fmac_f32_e32 v57, v142, v3
	v_fmac_f32_e32 v1, v132, v3
	v_add_u32_e32 v181, 0x1200, v137
	v_lshl_add_u64 v[152:153], v[144:145], 0, v[152:153]
	v_lshl_add_u64 v[156:157], v[144:145], 0, v[156:157]
	v_fmac_f32_e32 v57, v132, v56
	v_fmac_f32_e32 v58, v142, v1
	global_load_dwordx2 v[152:153], v[152:153], off offset:3072
	ds_write2_b32 v181, v0, v2 offset0:72 offset1:140
	global_load_dwordx2 v[156:157], v[156:157], off offset:3072
	v_cvt_pk_bf16_f32 v0, v3, v56
	v_fma_f32 v3, -v142, v57, v42
	v_fmac_f32_e32 v58, v132, v57
	v_cvt_pk_bf16_f32 v2, v1, v57
	v_fmac_f32_e32 v3, v132, v1
	v_fma_f32 v1, -v142, v58, v43
	v_permlane32_swap_b32_e32 v12, v60
	v_fmac_f32_e32 v59, v142, v3
	v_fmac_f32_e32 v1, v132, v3
	v_add_u32_e32 v182, 0x1400, v137
	v_permlane32_swap_b32_e32 v28, v44
	v_fmac_f32_e32 v59, v132, v58
	v_fmac_f32_e32 v12, v142, v1
	v_permlane32_swap_b32_e32 v29, v45
	ds_write2_b32 v182, v0, v2 offset0:80 offset1:148
	v_cvt_pk_bf16_f32 v0, v3, v58
	v_fma_f32 v3, -v142, v59, v28
	v_fmac_f32_e32 v12, v132, v59
	v_permlane32_swap_b32_e32 v13, v61
	v_cvt_pk_bf16_f32 v2, v1, v59
	v_fmac_f32_e32 v3, v132, v1
	v_fma_f32 v1, -v142, v12, v29
	v_permlane32_swap_b32_e32 v14, v62
	v_fmac_f32_e32 v13, v142, v3
	v_fmac_f32_e32 v1, v132, v3
	v_add_u32_e32 v183, 0x1600, v137
	v_permlane32_swap_b32_e32 v30, v46
	v_fmac_f32_e32 v13, v132, v12
	v_fmac_f32_e32 v14, v142, v1
	v_permlane32_swap_b32_e32 v31, v47
	ds_write2_b32 v183, v0, v2 offset0:88 offset1:156
	v_cvt_pk_bf16_f32 v0, v3, v12
	v_fma_f32 v3, -v142, v13, v30
	v_fmac_f32_e32 v14, v132, v13
	v_permlane32_swap_b32_e32 v15, v63
	v_cvt_pk_bf16_f32 v2, v1, v13
	v_fmac_f32_e32 v3, v132, v1
	v_fma_f32 v1, -v142, v14, v31
	v_fmac_f32_e32 v15, v142, v3
	v_fmac_f32_e32 v1, v132, v3
	v_add_u32_e32 v184, 0x1800, v137
	v_fmac_f32_e32 v15, v132, v14
	v_fmac_f32_e32 v60, v142, v1
	v_add_u32_e32 v185, 0x1a00, v137
	ds_write2_b32 v184, v0, v2 offset0:96 offset1:164
	v_cvt_pk_bf16_f32 v0, v3, v14
	v_cvt_pk_bf16_f32 v2, v1, v15
	v_fma_f32 v3, -v142, v15, v44
	v_fmac_f32_e32 v60, v132, v15
	ds_write2_b32 v185, v0, v2 offset0:104 offset1:172
	v_fmac_f32_e32 v3, v132, v1
	v_fma_f32 v2, -v142, v60, v45
	v_fmac_f32_e32 v61, v142, v3
	v_fmac_f32_e32 v2, v132, v3
	v_fmac_f32_e32 v61, v132, v60
	v_fmac_f32_e32 v62, v142, v2
	v_add_u32_e32 v186, 0x1c00, v137
	v_cvt_pk_bf16_f32 v1, v3, v60
	v_cvt_pk_bf16_f32 v3, v2, v61
	v_fma_f32 v0, -v142, v61, v46
	v_fmac_f32_e32 v62, v132, v61
	v_mov_b32_e32 v46, v63
	ds_write2_b32 v186, v1, v3 offset0:112 offset1:180
	v_fmac_f32_e32 v0, v132, v2
	v_mov_b32_e32 v1, v62
	v_cvt_pk_bf16_f32 v2, v0, v62
	v_mov_b32_e32 v63, v0
	v_pk_fma_f32 v[0:1], v[142:143], v[0:1], v[46:47]
	v_add_u32_e32 v187, 0x1e00, v137
	v_pk_fma_f32 v[128:129], v[132:133], v[62:63], v[0:1]
	v_add_u32_e32 v174, v159, v160
	v_cvt_pk_bf16_f32 v0, v129, v128
	ds_write2_b32 v187, v2, v0 offset0:120 offset1:188
	s_waitcnt lgkmcnt(0)
; #define LAS __attribute__((address_space(3)))
; __device__ __forceinline__ float bf2f(unsigned v) { return __uint_as_float(v << 16); }
; __device__ __forceinline__ unsigned pk2(float lo, float hi) { f32x2 v; v.x = lo; v.y = hi; return __builtin_bit_cast(unsigned, __builtin_convertvector(v, hwbf2)); }
; __device__ __forceinline__ void s5_passC_run(const Args& a, LAS unsigned char* wlds, int row0, int nblk, int g, int lane, float& hr, float& hi) {
;     ...
;         asm volatile("s_waitcnt lgkmcnt(0)" ::: "memory");
; #pragma unroll
;         for (int sb = 0; sb < 2; ++sb) {
;             f32x4 y = (f32x4){0.f, 0.f, 0.f, 0.f};
; #pragma unroll
;             for (int kb = 0; kb < 4; ++kb) { const bf16x8 hb = *(const LAS bf16x8*)(wlds + (sb * 16 + r16) * S5_LD + (32 * kb + 8 * q4) * 2);
;                 y = __builtin_amdgcn_mfma_f32_16x16x32_bf16(ca[kb], hb, y, 0, 0, 0); }
;             const int row = rb + sb * 16 + r16;
;             const u32x2 uu = uus[sb];
;             const float uv[4] = {bf2f(uu.x & 0xffff), bf2f(uu.x >> 16), bf2f(uu.y & 0xffff), bf2f(uu.y >> 16)};
;             float ge[4];
; #pragma unroll
;             for (int j = 0; j < 4; ++j) ge[j] = gelu_tanh(y[j] + dD[j] * uv[j]);
;             u32x2 gw; gw.x = pk2(ge[0], ge[1]); gw.y = pk2(ge[2], ge[3]);
;             const bf16x4 gbf = __builtin_bit_cast(bf16x4, gw);
;             const f32x4 o0 = __builtin_amdgcn_mfma_f32_16x16x16bf16_1k(ga[0], gbf, gb0, 0, 0, 0);
;             const f32x4 o1 = __builtin_amdgcn_mfma_f32_16x16x16bf16_1k(ga[1], gbf, gb1, 0, 0, 0);
;             float ov[4];
; #pragma unroll
;             for (int j = 0; j < 4; ++j) ov[j] = o0[j] * __builtin_amdgcn_rcpf(1.f + __builtin_amdgcn_exp2f(-1.4426950409f * o1[j]));
;             u32x2 ow; ow.x = pk2(ov[0], ov[1]); ow.y = pk2(ov[2], ov[3]);
;             *(u32x2*)(mixin + (size_t)row * DM + 512 + g * 16 + 4 * q4) = ow;
;         }
;         asm volatile("s_waitcnt lgkmcnt(0)" ::: "memory");
;         uus[0] = uun[0]; uus[1] = uun[1];
	ds_read_b128 v[0:3], v174
	ds_read_b128 v[4:7], v174 offset:64
	ds_read_b128 v[8:11], v174 offset:4352
	ds_read_b128 v[12:15], v174 offset:4416
	s_waitcnt lgkmcnt(3)
	v_mfma_f32_16x16x32_bf16 v[0:3], v[96:99], v[0:3], 0
	s_mov_b32 s3, s9
	v_lshl_add_u64 v[16:17], v[170:171], 0, s[2:3]
	v_lshl_add_u64 v[18:19], s[88:89], 0, v[172:173]
	s_waitcnt lgkmcnt(1)
	v_mfma_f32_16x16x32_bf16 v[8:11], v[96:99], v[8:11], 0
	v_lshl_add_u64 v[20:21], v[16:17], 0, v[112:113]
	v_lshl_add_u64 v[22:23], v[18:19], 0, s[2:3]
	v_add_co_u32_e32 v20, vcc, s55, v20
	v_mfma_f32_16x16x32_bf16 v[0:3], v[100:103], v[4:7], v[0:3]
	s_nop 0
	v_addc_co_u32_e32 v21, vcc, 0, v21, vcc
	v_add_u32_e32 v130, 32, v130
	s_waitcnt lgkmcnt(0)
	v_mfma_f32_16x16x32_bf16 v[4:7], v[100:103], v[12:15], v[8:11]
	s_nop 2
	ds_read_b128 v[8:11], v174 offset:128
	ds_read_b128 v[12:15], v174 offset:192
	s_mov_b32 s6, s4
	s_cmp_eq_u32 s4, 32
	s_waitcnt lgkmcnt(1)
	v_mfma_f32_16x16x32_bf16 v[0:3], v[104:107], v[8:11], v[0:3]
	ds_read_b128 v[8:11], v174 offset:4480
	ds_read_b128 v[16:19], v174 offset:4544
	s_waitcnt lgkmcnt(1)
	v_mfma_f32_16x16x32_bf16 v[4:7], v[104:107], v[8:11], v[4:7]
	v_mfma_f32_16x16x32_bf16 v[0:3], v[108:111], v[12:15], v[0:3]
	v_lshl_add_u64 v[12:13], v[22:23], 0, v[112:113]
	v_add_co_u32_e32 v22, vcc, 0x22c00000, v12
	s_waitcnt lgkmcnt(0)
	v_mfma_f32_16x16x32_bf16 v[4:7], v[108:111], v[16:19], v[4:7]
	v_addc_co_u32_e32 v23, vcc, 0, v13, vcc
	s_nop 2
	v_pk_fma_f32 v[0:1], v[68:69], v[146:147], v[0:1]
	v_pk_fma_f32 v[2:3], v[70:71], v[148:149], v[2:3]
	s_nop 0
	v_pk_mul_f32 v[10:11], v[2:3], v[2:3]
	v_pk_fma_f32 v[4:5], v[68:69], v[150:151], v[4:5]
	v_pk_fma_f32 v[8:9], v[70:71], v[154:155], v[6:7]
	v_pk_mul_f32 v[6:7], v[0:1], v[0:1]
	v_pk_mul_f32 v[14:15], v[4:5], v[4:5]
	v_pk_mul_f32 v[16:17], v[8:9], v[8:9]
	v_fmamk_f32 v6, v6, 0xbdd2d3e2, v163
	v_fmamk_f32 v7, v7, 0xbdd2d3e2, v163
	v_fmamk_f32 v10, v10, 0xbdd2d3e2, v163
	v_fmamk_f32 v11, v11, 0xbdd2d3e2, v163
	v_fmamk_f32 v12, v14, 0xbdd2d3e2, v163
	v_fmamk_f32 v14, v15, 0xbdd2d3e2, v163
	v_fmamk_f32 v15, v16, 0xbdd2d3e2, v163
	v_fmamk_f32 v16, v17, 0xbdd2d3e2, v163
	v_mul_f32_e32 v6, v0, v6
	v_mul_f32_e32 v7, v1, v7
	v_mul_f32_e32 v10, v2, v10
	v_mul_f32_e32 v11, v3, v11
	v_mul_f32_e32 v12, v4, v12
	v_mul_f32_e32 v14, v5, v14
	v_mul_f32_e32 v15, v8, v15
	v_mul_f32_e32 v16, v9, v16
	v_exp_f32_e32 v6, v6
	v_exp_f32_e32 v7, v7
	v_exp_f32_e32 v10, v10
	v_exp_f32_e32 v11, v11
	v_exp_f32_e32 v12, v12
	v_exp_f32_e32 v14, v14
	v_exp_f32_e32 v15, v15
	v_exp_f32_e32 v16, v16
	v_add_f32_e32 v6, 1.0, v6
	v_add_f32_e32 v7, 1.0, v7
	v_add_f32_e32 v10, 1.0, v10
	v_add_f32_e32 v11, 1.0, v11
	v_add_f32_e32 v12, 1.0, v12
	v_add_f32_e32 v17, 1.0, v14
	v_add_f32_e32 v18, 1.0, v15
	v_add_f32_e32 v19, 1.0, v16
	v_rcp_f32_e32 v6, v6
	v_rcp_f32_e32 v7, v7
	v_rcp_f32_e32 v10, v10
	v_rcp_f32_e32 v11, v11
	v_rcp_f32_e32 v14, v12
	v_rcp_f32_e32 v15, v17
	v_rcp_f32_e32 v16, v18
	v_rcp_f32_e32 v17, v19
	v_pk_mul_f32 v[0:1], v[0:1], v[6:7]
	v_pk_mul_f32 v[2:3], v[2:3], v[10:11]
	v_cvt_pk_bf16_f32 v6, v0, v1
	v_cvt_pk_bf16_f32 v7, v2, v3
	v_pk_mul_f32 v[10:11], v[4:5], v[14:15]
	v_pk_mul_f32 v[8:9], v[8:9], v[16:17]
	v_mfma_f32_16x16x16_bf16 v[0:3], v[138:139], v[6:7], v[72:75]
	v_cvt_pk_bf16_f32 v14, v10, v11
	v_cvt_pk_bf16_f32 v15, v8, v9
	v_mfma_f32_16x16x16_bf16 v[4:7], v[140:141], v[6:7], v[76:79]
	s_nop 0
	v_mfma_f32_16x16x16_bf16 v[8:11], v[138:139], v[14:15], v[72:75]
	v_mfma_f32_16x16x16_bf16 v[12:15], v[140:141], v[14:15], v[76:79]
	s_nop 4
	v_mul_f32_e32 v4, 0xbfb8aa3b, v4
	v_mul_f32_e32 v5, 0xbfb8aa3b, v5
	v_mul_f32_e32 v6, 0xbfb8aa3b, v6
	v_mul_f32_e32 v7, 0xbfb8aa3b, v7
	v_exp_f32_e32 v4, v4
	v_mul_f32_e32 v12, 0xbfb8aa3b, v12
	v_mul_f32_e32 v13, 0xbfb8aa3b, v13
	v_mul_f32_e32 v14, 0xbfb8aa3b, v14
	v_mul_f32_e32 v15, 0xbfb8aa3b, v15
	v_exp_f32_e32 v5, v5
	v_exp_f32_e32 v6, v6
	v_exp_f32_e32 v7, v7
	v_exp_f32_e32 v12, v12
	v_exp_f32_e32 v13, v13
	v_exp_f32_e32 v14, v14
	v_exp_f32_e32 v15, v15
	v_add_f32_e32 v4, 1.0, v4
	v_add_f32_e32 v5, 1.0, v5
	v_add_f32_e32 v6, 1.0, v6
	v_add_f32_e32 v7, 1.0, v7
	v_add_f32_e32 v12, 1.0, v12
	v_add_f32_e32 v13, 1.0, v13
	v_add_f32_e32 v14, 1.0, v14
	v_add_f32_e32 v15, 1.0, v15
	v_rcp_f32_e32 v4, v4
	v_rcp_f32_e32 v5, v5
	v_rcp_f32_e32 v6, v6
	v_rcp_f32_e32 v7, v7
	v_rcp_f32_e32 v12, v12
	v_rcp_f32_e32 v13, v13
	v_rcp_f32_e32 v14, v14
	v_rcp_f32_e32 v15, v15
	v_pk_mul_f32 v[0:1], v[0:1], v[4:5]
	v_pk_mul_f32 v[2:3], v[2:3], v[6:7]
	v_pk_mul_f32 v[4:5], v[8:9], v[12:13]
	v_pk_mul_f32 v[6:7], v[10:11], v[14:15]
	v_cvt_pk_bf16_f32 v0, v0, v1
	v_cvt_pk_bf16_f32 v1, v2, v3
	v_cvt_pk_bf16_f32 v2, v4, v5
	v_cvt_pk_bf16_f32 v3, v6, v7
	s_waitcnt vmcnt(0)
	v_mov_b32_e32 v32, v152
	v_mov_b32_e32 v33, v153
	v_mov_b32_e32 v48, v156
	v_mov_b32_e32 v49, v157
	global_store_dwordx2 v[20:21], v[0:1], off offset:1024
	global_store_dwordx2 v[22:23], v[2:3], off offset:1024
	s_waitcnt lgkmcnt(0)
	s_cbranch_scc0 .LBB0_892
	s_branch .LBB0_855
